# bundle: P6 expert-conversion loads issued together + P2a row-sumsq loads pipelined one iteration ahead, on top of the best version
# speedup vs baseline: 1.0075x; 1.0075x over previous
; DEVI float lo2f(uint32_t u) { return __uint_as_float(u << 16); }
; DEVI float hi2f(uint32_t u) { return __uint_as_float(u & 0xffff0000u); }
; DEVI void phase_p2(const int TIDX, const int BIDX, const int GDIM, KAP KA, unsigned char* WSB, float* OUTB, int l, unsigned char* smem) {
;     ...
;     for (int item = (BIDX & 7) * (GDIM >> 3) + (BIDX >> 3); item < 516 * 6; item += GDIM) {
;       const int mt = item / 6, nt = item % 6, m0 = mt * 128;
;       {
;         const int r = tid >> 1, hf = tid & 1;
;         const uint4* s = (const uint4*)(CQ + (size_t)(m0 + r) * 384 + hf * 192);
;         float ss = 0.f;
; #pragma unroll 4
;         for (int j = 0; j < 24; ++j) {
;           const uint4 u = s[j];
;           float a;
;           a = lo2f(u.x); ss += a * a; a = hi2f(u.x); ss += a * a;
;           a = lo2f(u.y); ss += a * a; a = hi2f(u.y); ss += a * a;
;           a = lo2f(u.z); ss += a * a; a = hi2f(u.z); ss += a * a;
;           a = lo2f(u.w); ss += a * a; a = hi2f(u.w); ss += a * a;
;         }
;         ss += __shfl_xor(ss, 1);
;         if (hf == 0) srow[r] = rsqrtf(ss * (1.f / 384.f) + EPS) * QSCALE;
.LBB0_363:
	s_mul_hi_i32 s11, s6, 0x2aaaaaab
	s_lshr_b32 s2, s11, 31
	s_add_i32 s11, s11, s2
	s_lshl_b32 s12, s11, 7
	v_add_u32_e32 v0, s12, v65
	v_mad_i64_i32 v[0:1], s[2:3], v0, s56, v[68:69]
	v_mov_b32_e32 v2, 0
	s_mov_b64 s[2:3], 0
	global_load_dwordx4 v[184:187], v[0:1], off offset:16
	global_load_dwordx4 v[188:191], v[0:1], off
	global_load_dwordx4 v[196:199], v[0:1], off offset:-16
	global_load_dwordx4 v[200:203], v[0:1], off offset:-32
.LBB0_364:
	s_waitcnt vmcnt(0)
	v_mov_b32_e32 v4, v184
	v_mov_b32_e32 v5, v185
	v_mov_b32_e32 v6, v186
	v_mov_b32_e32 v7, v187
	v_mov_b32_e32 v8, v188
	v_mov_b32_e32 v9, v189
	v_mov_b32_e32 v10, v190
	v_mov_b32_e32 v11, v191
	v_mov_b32_e32 v12, v196
	v_mov_b32_e32 v13, v197
	v_mov_b32_e32 v14, v198
	v_mov_b32_e32 v15, v199
	v_mov_b32_e32 v16, v200
	v_mov_b32_e32 v17, v201
	v_mov_b32_e32 v18, v202
	v_mov_b32_e32 v19, v203
	s_add_u32 s2, s2, 64
	s_addc_u32 s3, s3, 0
	v_lshl_add_u64 v[204:205], v[0:1], 0, s[2:3]
	global_load_dwordx4 v[184:187], v[204:205], off offset:16
	global_load_dwordx4 v[188:191], v[204:205], off
	global_load_dwordx4 v[196:199], v[204:205], off offset:-16
	global_load_dwordx4 v[200:203], v[204:205], off offset:-32
	s_cmpk_eq_i32 s2, 0x180
	v_lshlrev_b32_e32 v3, 16, v16
	v_lshlrev_b32_e32 v21, 16, v17
	v_and_b32_e32 v20, 0xffff0000, v16
	v_fmac_f32_e32 v2, v3, v3
	v_pk_mul_f32 v[20:21], v[20:21], v[20:21]
	v_and_b32_e32 v3, 0xffff0000, v17
	v_add_f32_e32 v2, v20, v2
	v_add_f32_e32 v16, v21, v2
	v_lshlrev_b32_e32 v2, 16, v18
	v_pk_mul_f32 v[2:3], v[2:3], v[2:3]
	s_nop 0
	v_add_f32_e32 v3, v3, v16
	v_add_f32_e32 v16, v2, v3
	v_lshlrev_b32_e32 v3, 16, v19
	v_and_b32_e32 v2, 0xffff0000, v18
	v_pk_mul_f32 v[2:3], v[2:3], v[2:3]
	s_nop 0
	v_add_f32_e32 v2, v2, v16
	v_add_f32_e32 v16, v3, v2
	v_and_b32_e32 v2, 0xffff0000, v19
	v_fmac_f32_e32 v16, v2, v2
	v_lshlrev_b32_e32 v2, 16, v12
	v_fmac_f32_e32 v16, v2, v2
	v_lshlrev_b32_e32 v3, 16, v13
	v_and_b32_e32 v2, 0xffff0000, v12
	v_pk_mul_f32 v[2:3], v[2:3], v[2:3]
	s_nop 0
	v_add_f32_e32 v2, v2, v16
	v_add_f32_e32 v12, v3, v2
	v_lshlrev_b32_e32 v2, 16, v14
	v_and_b32_e32 v3, 0xffff0000, v13
	v_pk_mul_f32 v[2:3], v[2:3], v[2:3]
	s_nop 0
	v_add_f32_e32 v3, v3, v12
	v_add_f32_e32 v12, v2, v3
	v_lshlrev_b32_e32 v3, 16, v15
	v_and_b32_e32 v2, 0xffff0000, v14
	v_pk_mul_f32 v[2:3], v[2:3], v[2:3]
	s_nop 0
	v_add_f32_e32 v2, v2, v12
	v_add_f32_e32 v12, v3, v2
	v_and_b32_e32 v2, 0xffff0000, v15
	v_fmac_f32_e32 v12, v2, v2
	v_lshlrev_b32_e32 v2, 16, v8
	v_fmac_f32_e32 v12, v2, v2
	v_lshlrev_b32_e32 v3, 16, v9
	v_and_b32_e32 v2, 0xffff0000, v8
	v_pk_mul_f32 v[2:3], v[2:3], v[2:3]
	s_nop 0
	v_add_f32_e32 v2, v2, v12
	v_add_f32_e32 v8, v3, v2
	v_lshlrev_b32_e32 v2, 16, v10
	v_and_b32_e32 v3, 0xffff0000, v9
	v_pk_mul_f32 v[2:3], v[2:3], v[2:3]
	s_nop 0
	v_add_f32_e32 v3, v3, v8
	v_add_f32_e32 v8, v2, v3
	v_lshlrev_b32_e32 v3, 16, v11
	v_and_b32_e32 v2, 0xffff0000, v10
	v_pk_mul_f32 v[2:3], v[2:3], v[2:3]
	s_nop 0
	v_add_f32_e32 v2, v2, v8
	v_add_f32_e32 v8, v3, v2
	v_and_b32_e32 v2, 0xffff0000, v11
	v_fmac_f32_e32 v8, v2, v2
	v_lshlrev_b32_e32 v2, 16, v4
	v_fmac_f32_e32 v8, v2, v2
	v_lshlrev_b32_e32 v3, 16, v5
	v_and_b32_e32 v2, 0xffff0000, v4
	v_pk_mul_f32 v[2:3], v[2:3], v[2:3]
	s_nop 0
	v_add_f32_e32 v2, v2, v8
	v_add_f32_e32 v4, v3, v2
	v_lshlrev_b32_e32 v2, 16, v6
	v_and_b32_e32 v3, 0xffff0000, v5
	v_pk_mul_f32 v[2:3], v[2:3], v[2:3]
	s_nop 0
	v_add_f32_e32 v3, v3, v4
	v_add_f32_e32 v4, v2, v3
	v_lshlrev_b32_e32 v3, 16, v7
	v_and_b32_e32 v2, 0xffff0000, v6
	v_pk_mul_f32 v[2:3], v[2:3], v[2:3]
	s_nop 0
	v_add_f32_e32 v2, v2, v4
	v_add_f32_e32 v2, v3, v2
	v_and_b32_e32 v3, 0xffff0000, v7
	v_fmac_f32_e32 v2, v3, v3
	s_cbranch_scc0 .LBB0_364
	ds_bpermute_b32 v0, v75, v2
	s_and_saveexec_b64 s[2:3], s[4:5]
	s_cbranch_execz .LBB0_367
	s_waitcnt lgkmcnt(0)
	v_add_f32_e32 v0, v2, v0
	v_fmamk_f32 v0, v0, 0x3b2aaaab, v228
	v_mul_f32_e32 v1, 0x4b800000, v0
	v_cmp_gt_f32_e32 vcc, s60, v0
	s_nop 1
	v_cndmask_b32_e32 v0, v0, v1, vcc
	v_rsq_f32_e32 v0, v0
	s_nop 0
	v_mul_f32_e32 v1, 0x45800000, v0
	v_cndmask_b32_e32 v0, v0, v1, vcc
	v_mul_f32_e32 v0, 0x3e16c740, v0
	ds_write_b32 v80, v0
